# static s_setprio 1 for waves 4-7 during the attention phase (dense + neighbourhood), reset to 0 at the phase end
# speedup vs baseline: 1.0037x; 1.0002x over previous
; __global__ void __launch_bounds__(512, 2) mk_fwd(Args args) {
;     ...
;     if (IN(6)) {
;         for (int vc = bx; vc < 256; vc += G) {
;             const int xcd = vc & 7, slot = vc >> 3;
;     ...
;             for (int j = 0; j < 3; ++j) {
;                 int b, kvh, hq, qb, seq; size_t tb;
;                 if (j == 0) { const int combo = xcd >> 1, idx = (xcd & 1) * 32 + slot; b = combo >> 1; kvh = combo & 1; hq = kvh * 4 + (idx >> 4); qb = idx & 15; tb = (size_t)b * 4096; seq = 4096; }
;                 else { const int combo = xcd * 2 + j - 1; b = combo >> 1; kvh = combo & 1; hq = kvh * 4 + (slot >> 3); qb = slot & 7; tb = (size_t)MP + (size_t)b * 2048; seq = 2048; }
;                 __syncthreads();
;                 att::attn_dense_body(QKV + (tb + qb * 256) * NQKV + hq * 128, QKV + tb * NQKV + 1024 + kvh * 128, QKV + tb * NQKV + 1280 + kvh * 128,
;                                      YAB + (tb + qb * 256) * DM + hq * 128, seq, (char*)lds);
;             }
.LBB0_520:
	v_readlane_b32 s2, v239, 35
	v_readlane_b32 s3, v239, 36
	s_cmp_lt_i32 s2, 7
	s_cselect_b64 s[2:3], -1, 0
	s_add_u32 s4, s70, 0x1ab80000
	v_writelane_b32 v239, s4, 48
	s_addc_u32 s4, s71, 0
	s_and_b64 s[2:3], s[2:3], s[0:1]
	v_writelane_b32 v239, s4, 49
	s_andn2_b64 vcc, exec, s[2:3]
	v_writelane_b32 v239, s61, 50
	s_cbranch_vccnz .LBB0_573
	v_writelane_b32 v239, s2, 51
	s_mov_b32 s64, s96
	s_cmpk_gt_i32 s61, 0xff
	v_writelane_b32 v239, s3, 52
	v_writelane_b32 v239, s63, 53
	v_writelane_b32 v239, s64, 54
	s_nop 1
	v_writelane_b32 v239, s65, 55
	s_cbranch_scc1 .LBB0_572
	v_readfirstlane_b32 s0, v177
	s_nop 3
	s_lshr_b32 s0, s0, 8
	s_cmp_lg_u32 s0, 0
	s_cbranch_scc0 .Lattn_prio_done
	s_setprio 1
.Lattn_prio_done:
	v_readlane_b32 s0, v239, 27
	v_readlane_b32 s6, v239, 33
	v_readlane_b32 s1, v239, 28
	v_readlane_b32 s7, v239, 34
	s_add_u32 s0, s6, 0xd608a00
	s_addc_u32 s1, s7, 0
	v_readlane_b32 s2, v239, 29
	v_readlane_b32 s3, v239, 30
	v_readlane_b32 s4, v239, 31
	v_readlane_b32 s5, v239, 32
	v_writelane_b32 v239, s0, 56
	s_waitcnt lgkmcnt(0)
	s_mov_b32 s80, 0
	s_movk_i32 s79, 0x2400
	v_writelane_b32 v239, s1, 57
	s_add_u32 s0, s6, 0xd459c00
	v_writelane_b32 v239, s0, 58
	s_addc_u32 s0, s7, 0
	v_writelane_b32 v239, s0, 59
	s_add_i32 s0, 0, 0x10000
	v_writelane_b32 v239, s0, 60
	s_add_i32 s0, 0, 0x10800
	v_mov_b32_e32 v179, 0
	s_movk_i32 s33, 0x1200
	s_mov_b32 s70, 0x42b504f3
	s_mov_b32 s78, 0x3e0293ee
	v_mov_b32_e32 v188, 0xf149f2ca
	s_mov_b64 s[26:27], 0x8000
	s_mov_b64 s[28:29], 0x9000
	s_mov_b64 s[30:31], 0xa000
	s_mov_b64 s[34:35], 0xb000
	s_mov_b64 s[36:37], 0x10000
	s_mov_b64 s[38:39], 0x11000
	s_mov_b64 s[40:41], 0x12000
	s_mov_b64 s[42:43], 0x13000
	s_mov_b64 s[44:45], 0x18000
	s_mov_b64 s[46:47], 0x19000
	s_mov_b64 s[48:49], 0x1a000
	s_mov_b64 s[50:51], 0x1b000
	v_writelane_b32 v239, s0, 61
	v_mov_b64_e32 v[180:181], 0x24000
	v_mov_b32_e32 v189, 0x10b64
	v_mov_b32_e32 v190, 0x10ba0
	v_mov_b32_e32 v191, 0x90000
	s_mov_b32 s52, s61
	v_writelane_b32 v239, s61, 62
	s_branch .LBB0_524

; #define SEAM(k) do { } while (0)
; #define SEAM(k) do { if (IN(k) && IN((k) + 1)) { if ((k) == 0) cg::this_grid().sync(); else xcd_barrier(xbar); } } while (0)
; __global__ void __launch_bounds__(512, 2) mk_fwd(Args args) {
;     ...
;         }
;         __syncthreads();
;     }
;     SEAM(6);
.LBB0_572:
	s_setprio 0
	v_readlane_b32 s0, v239, 27
	v_readlane_b32 s2, v239, 29
	v_readlane_b32 s3, v239, 30
	v_readlane_b32 s6, v239, 33
	v_readlane_b32 s7, v239, 34
	v_readlane_b32 s64, v239, 54
	v_readlane_b32 s4, v239, 31
	v_readlane_b32 s5, v239, 32
	s_mov_b64 s[70:71], s[6:7]
	s_mov_b64 s[66:67], s[2:3]
	v_readlane_b32 s2, v239, 51
	s_mov_b32 s96, s64
	v_readlane_b32 s63, v239, 53
	s_mov_b64 s[68:69], s[4:5]
	v_readlane_b32 s97, v239, 37
	v_readlane_b32 s3, v239, 52
	s_waitcnt lgkmcnt(0)
	s_barrier
	v_readlane_b32 s65, v239, 55
	v_readlane_b32 s1, v239, 28
